# GEMM K-loops (4 loops): loop-carried scalar updates and exit test moved in front of the loop-back barrier; at the loop head the LDS fragment reads issue first with the scalar address selects in their
# baseline (speedup 1.0000x reference)
.LBB0_29:
	v_add_u32_e32 v142, 0x10000, v179
	v_add_u32_e32 v168, 0x14000, v179
	ds_read_b128 v[130:133], v142
	ds_read_b128 v[134:137], v142 offset:1024
	ds_read_b128 v[138:141], v142 offset:2048
	ds_read_b128 v[142:145], v142 offset:3072
	ds_read_b128 v[146:149], v168
	ds_read_b128 v[160:163], v168 offset:1024
	ds_read_b128 v[164:167], v168 offset:2048
	ds_read_b128 v[168:171], v168 offset:3072
	s_add_u32 s12, s0, 0xfffc0080
	s_addc_u32 s13, s1, -1
	s_add_i32 s14, 0, 0x10000
	s_cmp_eq_u32 s11, 12
	s_cselect_b32 s37, s5, s13
	s_cselect_b32 s36, s6, s12
	s_cselect_b32 s29, s7, s10
	s_cselect_b32 s28, s8, s9
	s_add_i32 s15, 0, 0x14000
	s_mov_b32 m0, s80
	v_lshl_add_u64 v[208:209], s[0:1], 0, v[156:157]
	ds_read_b128 v[172:175], v182
	ds_read_b128 v[184:187], v182 offset:1024
	ds_read_b128 v[188:191], v182 offset:2048
	ds_read_b128 v[192:195], v182 offset:3072
	ds_read_b128 v[196:199], v182 offset:4096
	ds_read_b128 v[200:203], v182 offset:5120
	ds_read_b128 v[204:207], v182 offset:6144
	ds_read_b128 v[226:229], v182 offset:7168
	global_load_lds_dwordx4 v[208:209], off
	v_lshl_add_u64 v[208:209], s[0:1], 0, v[158:159]
	s_add_i32 m0, s25, 0xe000
	s_nop 0
	global_load_lds_dwordx4 v[208:209], off
	s_waitcnt vmcnt(8)
	s_waitcnt lgkmcnt(0)
	s_barrier
	s_setprio 1
	s_waitcnt lgkmcnt(0)
	v_mfma_f32_16x16x32_bf16 v[126:129], v[130:133], v[172:175], v[126:129]
	v_mfma_f32_16x16x32_bf16 v[122:125], v[138:141], v[172:175], v[122:125]
	v_mfma_f32_16x16x32_bf16 v[110:113], v[130:133], v[188:191], v[110:113]
	v_mfma_f32_16x16x32_bf16 v[106:109], v[138:141], v[188:191], v[106:109]
	v_mfma_f32_16x16x32_bf16 v[94:97], v[130:133], v[196:199], v[94:97]
	v_mfma_f32_16x16x32_bf16 v[90:93], v[138:141], v[196:199], v[90:93]
	v_mfma_f32_16x16x32_bf16 v[78:81], v[130:133], v[204:207], v[78:81]
	v_mfma_f32_16x16x32_bf16 v[74:77], v[138:141], v[204:207], v[74:77]
	v_mfma_f32_16x16x32_bf16 v[126:129], v[134:137], v[184:187], v[126:129]
	v_mfma_f32_16x16x32_bf16 v[122:125], v[142:145], v[184:187], v[122:125]
	v_mfma_f32_16x16x32_bf16 v[110:113], v[134:137], v[192:195], v[110:113]
	v_mfma_f32_16x16x32_bf16 v[106:109], v[142:145], v[192:195], v[106:109]
	v_mfma_f32_16x16x32_bf16 v[94:97], v[134:137], v[200:203], v[94:97]
	v_mfma_f32_16x16x32_bf16 v[90:93], v[142:145], v[200:203], v[90:93]
	v_mfma_f32_16x16x32_bf16 v[78:81], v[134:137], v[226:229], v[78:81]
	v_mfma_f32_16x16x32_bf16 v[74:77], v[142:145], v[226:229], v[74:77]
	s_setprio 0
	s_setprio 1
	v_mfma_f32_16x16x32_bf16 v[118:121], v[146:149], v[172:175], v[118:121]
	v_mfma_f32_16x16x32_bf16 v[114:117], v[164:167], v[172:175], v[114:117]
	v_mfma_f32_16x16x32_bf16 v[102:105], v[146:149], v[188:191], v[102:105]
	v_mfma_f32_16x16x32_bf16 v[98:101], v[164:167], v[188:191], v[98:101]
	v_mfma_f32_16x16x32_bf16 v[86:89], v[146:149], v[196:199], v[86:89]
	v_mfma_f32_16x16x32_bf16 v[82:85], v[164:167], v[196:199], v[82:85]
	v_mfma_f32_16x16x32_bf16 v[70:73], v[146:149], v[204:207], v[70:73]
	v_mfma_f32_16x16x32_bf16 v[66:69], v[164:167], v[204:207], v[66:69]
	v_mfma_f32_16x16x32_bf16 v[118:121], v[160:163], v[184:187], v[118:121]
	v_mfma_f32_16x16x32_bf16 v[114:117], v[168:171], v[184:187], v[114:117]
	v_mfma_f32_16x16x32_bf16 v[102:105], v[160:163], v[192:195], v[102:105]
	v_mfma_f32_16x16x32_bf16 v[98:101], v[168:171], v[192:195], v[98:101]
	v_mfma_f32_16x16x32_bf16 v[86:89], v[160:163], v[200:203], v[86:89]
	v_mfma_f32_16x16x32_bf16 v[82:85], v[168:171], v[200:203], v[82:85]
	v_mfma_f32_16x16x32_bf16 v[70:73], v[160:163], v[226:229], v[70:73]
	v_mfma_f32_16x16x32_bf16 v[66:69], v[168:171], v[226:229], v[66:69]
	s_setprio 0
	s_barrier
	s_add_i32 s12, s14, s38
	v_lshl_add_u64 v[208:209], s[28:29], 0, v[64:65]
	s_mov_b32 m0, s12
	ds_read_b128 v[172:175], v182 offset:16384
	ds_read_b128 v[184:187], v182 offset:17408
	ds_read_b128 v[188:191], v182 offset:18432
	ds_read_b128 v[192:195], v182 offset:19456
	ds_read_b128 v[196:199], v182 offset:20480
	ds_read_b128 v[200:203], v182 offset:21504
	ds_read_b128 v[204:207], v182 offset:22528
	ds_read_b128 v[226:229], v182 offset:23552
	global_load_lds_dwordx4 v[208:209], off
	s_add_i32 m0, s12, 0x2000
	s_add_u32 s12, s28, 0x40000
	v_lshl_add_u64 v[210:211], s[28:29], 0, v[150:151]
	s_addc_u32 s13, s29, 0
	s_add_i32 s14, s15, s38
	global_load_lds_dwordx4 v[210:211], off
	v_lshl_add_u64 v[212:213], s[12:13], 0, v[64:65]
	s_mov_b32 m0, s14
	v_lshl_add_u64 v[218:219], s[36:37], 0, v[152:153]
	global_load_lds_dwordx4 v[212:213], off
	v_lshl_add_u64 v[212:213], s[12:13], 0, v[150:151]
	s_add_i32 m0, s14, 0x2000
	v_readlane_b32 s12, v251, 21
	global_load_lds_dwordx4 v[212:213], off
	v_lshl_add_u64 v[212:213], s[36:37], 0, v[154:155]
	s_mov_b32 m0, s25
	s_nop 0
	global_load_lds_dwordx4 v[212:213], off
	s_mov_b32 m0, s12
	s_nop 0
	global_load_lds_dwordx4 v[218:219], off
	s_waitcnt vmcnt(8)
	s_waitcnt lgkmcnt(0)
	s_barrier
	s_setprio 1
	s_waitcnt lgkmcnt(0)
	v_mfma_f32_16x16x32_bf16 v[60:63], v[130:133], v[172:175], v[60:63]
	v_mfma_f32_16x16x32_bf16 v[56:59], v[138:141], v[172:175], v[56:59]
	v_mfma_f32_16x16x32_bf16 v[44:47], v[130:133], v[188:191], v[44:47]
	v_mfma_f32_16x16x32_bf16 v[40:43], v[138:141], v[188:191], v[40:43]
	v_mfma_f32_16x16x32_bf16 v[28:31], v[130:133], v[196:199], v[28:31]
	v_mfma_f32_16x16x32_bf16 v[24:27], v[138:141], v[196:199], v[24:27]
	v_mfma_f32_16x16x32_bf16 v[12:15], v[130:133], v[204:207], v[12:15]
	v_mfma_f32_16x16x32_bf16 v[8:11], v[138:141], v[204:207], v[8:11]
	v_mfma_f32_16x16x32_bf16 v[60:63], v[134:137], v[184:187], v[60:63]
	v_mfma_f32_16x16x32_bf16 v[56:59], v[142:145], v[184:187], v[56:59]
	v_mfma_f32_16x16x32_bf16 v[44:47], v[134:137], v[192:195], v[44:47]
	v_mfma_f32_16x16x32_bf16 v[40:43], v[142:145], v[192:195], v[40:43]
	v_mfma_f32_16x16x32_bf16 v[28:31], v[134:137], v[200:203], v[28:31]
	v_mfma_f32_16x16x32_bf16 v[24:27], v[142:145], v[200:203], v[24:27]
	v_mfma_f32_16x16x32_bf16 v[12:15], v[134:137], v[226:229], v[12:15]
	v_mfma_f32_16x16x32_bf16 v[8:11], v[142:145], v[226:229], v[8:11]
	s_setprio 0
	s_setprio 1
	v_mfma_f32_16x16x32_bf16 v[52:55], v[146:149], v[172:175], v[52:55]
	v_mfma_f32_16x16x32_bf16 v[48:51], v[164:167], v[172:175], v[48:51]
	v_mfma_f32_16x16x32_bf16 v[36:39], v[146:149], v[188:191], v[36:39]
	v_mfma_f32_16x16x32_bf16 v[32:35], v[164:167], v[188:191], v[32:35]
	v_mfma_f32_16x16x32_bf16 v[20:23], v[146:149], v[196:199], v[20:23]
	v_mfma_f32_16x16x32_bf16 v[16:19], v[164:167], v[196:199], v[16:19]
	v_mfma_f32_16x16x32_bf16 v[4:7], v[146:149], v[204:207], v[4:7]
	v_mfma_f32_16x16x32_bf16 v[0:3], v[164:167], v[204:207], v[0:3]
	v_mfma_f32_16x16x32_bf16 v[52:55], v[160:163], v[184:187], v[52:55]
	v_mfma_f32_16x16x32_bf16 v[48:51], v[168:171], v[184:187], v[48:51]
	v_mfma_f32_16x16x32_bf16 v[36:39], v[160:163], v[192:195], v[36:39]
	v_mfma_f32_16x16x32_bf16 v[32:35], v[168:171], v[192:195], v[32:35]
	v_mfma_f32_16x16x32_bf16 v[20:23], v[160:163], v[200:203], v[20:23]
	v_mfma_f32_16x16x32_bf16 v[16:19], v[168:171], v[200:203], v[16:19]
	v_mfma_f32_16x16x32_bf16 v[4:7], v[160:163], v[226:229], v[4:7]
	v_mfma_f32_16x16x32_bf16 v[0:3], v[168:171], v[226:229], v[0:3]
	s_setprio 0
	s_barrier
	s_add_i32 s14, 0, 0x18000
	s_add_i32 s15, 0, 0x1c000
	v_add_u32_e32 v142, s14, v179
	v_add_u32_e32 v168, s15, v179
	ds_read_b128 v[130:133], v142
	ds_read_b128 v[134:137], v142 offset:1024
	ds_read_b128 v[138:141], v142 offset:2048
	ds_read_b128 v[142:145], v142 offset:3072
	ds_read_b128 v[146:149], v168
	ds_read_b128 v[160:163], v168 offset:1024
	ds_read_b128 v[164:167], v168 offset:2048
	ds_read_b128 v[168:171], v168 offset:3072
	s_add_u32 s12, s36, 0x40000
	s_addc_u32 s13, s37, 0
	s_mov_b32 m0, s75
	v_lshl_add_u64 v[230:231], s[12:13], 0, v[154:155]
	ds_read_b128 v[172:175], v182 offset:32768
	ds_read_b128 v[184:187], v182 offset:33792
	ds_read_b128 v[188:191], v182 offset:34816
	ds_read_b128 v[192:195], v182 offset:35840
	ds_read_b128 v[196:199], v182 offset:36864
	ds_read_b128 v[200:203], v182 offset:37888
	ds_read_b128 v[204:207], v182 offset:38912
	ds_read_b128 v[226:229], v182 offset:39936
	global_load_lds_dwordx4 v[230:231], off
	v_lshl_add_u64 v[230:231], s[12:13], 0, v[152:153]
	s_mov_b32 m0, s74
	s_nop 0
	global_load_lds_dwordx4 v[230:231], off
	s_waitcnt vmcnt(8)
	s_waitcnt lgkmcnt(0)
	s_barrier
	s_setprio 1
	s_waitcnt lgkmcnt(0)
	v_mfma_f32_16x16x32_bf16 v[126:129], v[130:133], v[172:175], v[126:129]
	v_mfma_f32_16x16x32_bf16 v[122:125], v[138:141], v[172:175], v[122:125]
	v_mfma_f32_16x16x32_bf16 v[110:113], v[130:133], v[188:191], v[110:113]
	v_mfma_f32_16x16x32_bf16 v[106:109], v[138:141], v[188:191], v[106:109]
	v_mfma_f32_16x16x32_bf16 v[94:97], v[130:133], v[196:199], v[94:97]
	v_mfma_f32_16x16x32_bf16 v[90:93], v[138:141], v[196:199], v[90:93]
	v_mfma_f32_16x16x32_bf16 v[78:81], v[130:133], v[204:207], v[78:81]
	v_mfma_f32_16x16x32_bf16 v[74:77], v[138:141], v[204:207], v[74:77]
	v_mfma_f32_16x16x32_bf16 v[126:129], v[134:137], v[184:187], v[126:129]
	v_mfma_f32_16x16x32_bf16 v[122:125], v[142:145], v[184:187], v[122:125]
	v_mfma_f32_16x16x32_bf16 v[110:113], v[134:137], v[192:195], v[110:113]
	v_mfma_f32_16x16x32_bf16 v[106:109], v[142:145], v[192:195], v[106:109]
	v_mfma_f32_16x16x32_bf16 v[94:97], v[134:137], v[200:203], v[94:97]
	v_mfma_f32_16x16x32_bf16 v[90:93], v[142:145], v[200:203], v[90:93]
	v_mfma_f32_16x16x32_bf16 v[78:81], v[134:137], v[226:229], v[78:81]
	v_mfma_f32_16x16x32_bf16 v[74:77], v[142:145], v[226:229], v[74:77]
	s_setprio 0
	s_setprio 1
	v_mfma_f32_16x16x32_bf16 v[118:121], v[146:149], v[172:175], v[118:121]
	v_mfma_f32_16x16x32_bf16 v[114:117], v[164:167], v[172:175], v[114:117]
	v_mfma_f32_16x16x32_bf16 v[102:105], v[146:149], v[188:191], v[102:105]
	v_mfma_f32_16x16x32_bf16 v[98:101], v[164:167], v[188:191], v[98:101]
	v_mfma_f32_16x16x32_bf16 v[86:89], v[146:149], v[196:199], v[86:89]
	v_mfma_f32_16x16x32_bf16 v[82:85], v[164:167], v[196:199], v[82:85]
	v_mfma_f32_16x16x32_bf16 v[70:73], v[146:149], v[204:207], v[70:73]
	v_mfma_f32_16x16x32_bf16 v[66:69], v[164:167], v[204:207], v[66:69]
	v_mfma_f32_16x16x32_bf16 v[118:121], v[160:163], v[184:187], v[118:121]
	v_mfma_f32_16x16x32_bf16 v[114:117], v[168:171], v[184:187], v[114:117]
	v_mfma_f32_16x16x32_bf16 v[102:105], v[160:163], v[192:195], v[102:105]
	v_mfma_f32_16x16x32_bf16 v[98:101], v[168:171], v[192:195], v[98:101]
	v_mfma_f32_16x16x32_bf16 v[86:89], v[160:163], v[200:203], v[86:89]
	v_mfma_f32_16x16x32_bf16 v[82:85], v[168:171], v[200:203], v[82:85]
	v_mfma_f32_16x16x32_bf16 v[70:73], v[160:163], v[226:229], v[70:73]
	v_mfma_f32_16x16x32_bf16 v[66:69], v[168:171], v[226:229], v[66:69]
	s_setprio 0
	s_barrier
	s_add_i32 s12, s14, s38
	v_lshl_add_u64 v[208:209], v[208:209], 0, s[40:41]
	s_mov_b32 m0, s12
	ds_read_b128 v[172:175], v182 offset:49152
	ds_read_b128 v[184:187], v182 offset:50176
	ds_read_b128 v[188:191], v182 offset:51200
	ds_read_b128 v[192:195], v182 offset:52224
	ds_read_b128 v[196:199], v182 offset:53248
	ds_read_b128 v[200:203], v182 offset:54272
	ds_read_b128 v[204:207], v182 offset:55296
	ds_read_b128 v[226:229], v182 offset:56320
	global_load_lds_dwordx4 v[208:209], off
	s_add_i32 m0, s12, 0x2000
	s_add_u32 s12, s28, 0x40080
	v_lshl_add_u64 v[208:209], v[210:211], 0, s[40:41]
	s_addc_u32 s13, s29, 0
	s_add_i32 s14, s15, s38
	global_load_lds_dwordx4 v[208:209], off
	v_lshl_add_u64 v[208:209], s[12:13], 0, v[64:65]
	s_mov_b32 m0, s14
	s_nop 0
	global_load_lds_dwordx4 v[208:209], off
	v_lshl_add_u64 v[208:209], s[12:13], 0, v[150:151]
	s_add_i32 m0, s14, 0x2000
	s_nop 0
	global_load_lds_dwordx4 v[208:209], off
	v_lshl_add_u64 v[208:209], v[212:213], 0, s[40:41]
	s_mov_b32 m0, s92
	s_nop 0
	global_load_lds_dwordx4 v[208:209], off
	v_lshl_add_u64 v[208:209], v[218:219], 0, s[40:41]
	s_mov_b32 m0, s78
	s_nop 0
	global_load_lds_dwordx4 v[208:209], off
	s_waitcnt vmcnt(8)
	s_waitcnt lgkmcnt(0)
	s_barrier
	s_setprio 1
	s_waitcnt lgkmcnt(0)
	v_mfma_f32_16x16x32_bf16 v[60:63], v[130:133], v[172:175], v[60:63]
	v_mfma_f32_16x16x32_bf16 v[56:59], v[138:141], v[172:175], v[56:59]
	v_mfma_f32_16x16x32_bf16 v[44:47], v[130:133], v[188:191], v[44:47]
	v_mfma_f32_16x16x32_bf16 v[40:43], v[138:141], v[188:191], v[40:43]
	v_mfma_f32_16x16x32_bf16 v[28:31], v[130:133], v[196:199], v[28:31]
	v_mfma_f32_16x16x32_bf16 v[24:27], v[138:141], v[196:199], v[24:27]
	v_mfma_f32_16x16x32_bf16 v[12:15], v[130:133], v[204:207], v[12:15]
	v_mfma_f32_16x16x32_bf16 v[8:11], v[138:141], v[204:207], v[8:11]
	v_mfma_f32_16x16x32_bf16 v[60:63], v[134:137], v[184:187], v[60:63]
	v_mfma_f32_16x16x32_bf16 v[56:59], v[142:145], v[184:187], v[56:59]
	v_mfma_f32_16x16x32_bf16 v[44:47], v[134:137], v[192:195], v[44:47]
	v_mfma_f32_16x16x32_bf16 v[40:43], v[142:145], v[192:195], v[40:43]
	v_mfma_f32_16x16x32_bf16 v[28:31], v[134:137], v[200:203], v[28:31]
	v_mfma_f32_16x16x32_bf16 v[24:27], v[142:145], v[200:203], v[24:27]
	v_mfma_f32_16x16x32_bf16 v[12:15], v[134:137], v[226:229], v[12:15]
	v_mfma_f32_16x16x32_bf16 v[8:11], v[142:145], v[226:229], v[8:11]
	s_setprio 0
	s_setprio 1
	v_mfma_f32_16x16x32_bf16 v[52:55], v[146:149], v[172:175], v[52:55]
	v_mfma_f32_16x16x32_bf16 v[48:51], v[164:167], v[172:175], v[48:51]
	v_mfma_f32_16x16x32_bf16 v[36:39], v[146:149], v[188:191], v[36:39]
	v_mfma_f32_16x16x32_bf16 v[32:35], v[164:167], v[188:191], v[32:35]
	v_mfma_f32_16x16x32_bf16 v[20:23], v[146:149], v[196:199], v[20:23]
	v_mfma_f32_16x16x32_bf16 v[16:19], v[164:167], v[196:199], v[16:19]
	v_mfma_f32_16x16x32_bf16 v[4:7], v[146:149], v[204:207], v[4:7]
	v_mfma_f32_16x16x32_bf16 v[0:3], v[164:167], v[204:207], v[0:3]
	v_mfma_f32_16x16x32_bf16 v[52:55], v[160:163], v[184:187], v[52:55]
	v_mfma_f32_16x16x32_bf16 v[48:51], v[168:171], v[184:187], v[48:51]
	v_mfma_f32_16x16x32_bf16 v[36:39], v[160:163], v[192:195], v[36:39]
	v_mfma_f32_16x16x32_bf16 v[32:35], v[168:171], v[192:195], v[32:35]
	v_mfma_f32_16x16x32_bf16 v[20:23], v[160:163], v[200:203], v[20:23]
	v_mfma_f32_16x16x32_bf16 v[16:19], v[168:171], v[200:203], v[16:19]
	v_mfma_f32_16x16x32_bf16 v[4:7], v[160:163], v[226:229], v[4:7]
	v_mfma_f32_16x16x32_bf16 v[0:3], v[168:171], v[226:229], v[0:3]
	s_setprio 0
	s_add_i32 s11, s11, 2
	s_add_u32 s0, s0, 0x100
	s_addc_u32 s1, s1, 0
	s_add_u32 s9, s9, 0x100
	s_addc_u32 s10, s10, 0
	s_cmp_gt_u32 s11, 13
	s_barrier
	s_cbranch_scc0 .LBB0_29
	s_and_b64 vcc, exec, s[22:23]
	s_cbranch_vccz .LBB0_32
	s_barrier

.LBB0_51:
	v_add_u32_e32 v158, 0x10000, v144
	v_add_u32_e32 v162, 0x14000, v144
	ds_read_b128 v[146:149], v158
	ds_read_b128 v[150:153], v158 offset:1024
	ds_read_b128 v[154:157], v158 offset:2048
	ds_read_b128 v[158:161], v158 offset:3072
	ds_read_b128 v[166:169], v162
	ds_read_b128 v[170:173], v162 offset:1024
	ds_read_b128 v[174:177], v162 offset:2048
	ds_read_b128 v[178:181], v162 offset:3072
	s_add_u32 s12, s22, s52
	s_addc_u32 s13, s23, s53
	s_add_u32 s12, s12, 0x100
	s_addc_u32 s13, s13, 0
	s_add_u32 s14, s5, s52
	s_addc_u32 s15, s6, s53
	s_add_i32 s16, 0, 0x10000
	s_cmpk_eq_i32 s52, 0x700
	s_cselect_b32 s37, s7, s13
	s_cselect_b32 s36, s8, s12
	s_cselect_b32 s29, s9, s15
	s_cselect_b32 s28, s10, s14
	s_add_i32 s14, 0, 0x14000
	s_mov_b32 m0, s80
	v_lshl_add_u64 v[162:163], v[140:141], 0, s[52:53]
	ds_read_b128 v[182:185], v145
	ds_read_b128 v[186:189], v145 offset:1024
	ds_read_b128 v[190:193], v145 offset:2048
	ds_read_b128 v[194:197], v145 offset:3072
	ds_read_b128 v[198:201], v145 offset:4096
	ds_read_b128 v[202:205], v145 offset:5120
	ds_read_b128 v[206:209], v145 offset:6144
	ds_read_b128 v[226:229], v145 offset:7168
	global_load_lds_dwordx4 v[162:163], off
	v_lshl_add_u64 v[162:163], v[142:143], 0, s[52:53]
	s_add_i32 m0, s25, 0xe000
	s_nop 0
	global_load_lds_dwordx4 v[162:163], off
	s_waitcnt vmcnt(8)
	s_waitcnt lgkmcnt(0)
	s_barrier
	s_setprio 1
	s_waitcnt lgkmcnt(0)
	v_mfma_f32_16x16x32_bf16 v[126:129], v[146:149], v[182:185], v[126:129]
	v_mfma_f32_16x16x32_bf16 v[122:125], v[154:157], v[182:185], v[122:125]
	v_mfma_f32_16x16x32_bf16 v[110:113], v[146:149], v[190:193], v[110:113]
	v_mfma_f32_16x16x32_bf16 v[106:109], v[154:157], v[190:193], v[106:109]
	v_mfma_f32_16x16x32_bf16 v[94:97], v[146:149], v[198:201], v[94:97]
	v_mfma_f32_16x16x32_bf16 v[90:93], v[154:157], v[198:201], v[90:93]
	v_mfma_f32_16x16x32_bf16 v[78:81], v[146:149], v[206:209], v[78:81]
	v_mfma_f32_16x16x32_bf16 v[74:77], v[154:157], v[206:209], v[74:77]
	v_mfma_f32_16x16x32_bf16 v[126:129], v[150:153], v[186:189], v[126:129]
	v_mfma_f32_16x16x32_bf16 v[122:125], v[158:161], v[186:189], v[122:125]
	v_mfma_f32_16x16x32_bf16 v[110:113], v[150:153], v[194:197], v[110:113]
	v_mfma_f32_16x16x32_bf16 v[106:109], v[158:161], v[194:197], v[106:109]
	v_mfma_f32_16x16x32_bf16 v[94:97], v[150:153], v[202:205], v[94:97]
	v_mfma_f32_16x16x32_bf16 v[90:93], v[158:161], v[202:205], v[90:93]
	v_mfma_f32_16x16x32_bf16 v[78:81], v[150:153], v[226:229], v[78:81]
	v_mfma_f32_16x16x32_bf16 v[74:77], v[158:161], v[226:229], v[74:77]
	s_setprio 0
	s_setprio 1
	v_mfma_f32_16x16x32_bf16 v[118:121], v[166:169], v[182:185], v[118:121]
	v_mfma_f32_16x16x32_bf16 v[114:117], v[174:177], v[182:185], v[114:117]
	v_mfma_f32_16x16x32_bf16 v[102:105], v[166:169], v[190:193], v[102:105]
	v_mfma_f32_16x16x32_bf16 v[98:101], v[174:177], v[190:193], v[98:101]
	v_mfma_f32_16x16x32_bf16 v[86:89], v[166:169], v[198:201], v[86:89]
	v_mfma_f32_16x16x32_bf16 v[82:85], v[174:177], v[198:201], v[82:85]
	v_mfma_f32_16x16x32_bf16 v[70:73], v[166:169], v[206:209], v[70:73]
	v_mfma_f32_16x16x32_bf16 v[66:69], v[174:177], v[206:209], v[66:69]
	v_mfma_f32_16x16x32_bf16 v[118:121], v[170:173], v[186:189], v[118:121]
	v_mfma_f32_16x16x32_bf16 v[114:117], v[178:181], v[186:189], v[114:117]
	v_mfma_f32_16x16x32_bf16 v[102:105], v[170:173], v[194:197], v[102:105]
	v_mfma_f32_16x16x32_bf16 v[98:101], v[178:181], v[194:197], v[98:101]
	v_mfma_f32_16x16x32_bf16 v[86:89], v[170:173], v[202:205], v[86:89]
	v_mfma_f32_16x16x32_bf16 v[82:85], v[178:181], v[202:205], v[82:85]
	v_mfma_f32_16x16x32_bf16 v[70:73], v[170:173], v[226:229], v[70:73]
	v_mfma_f32_16x16x32_bf16 v[66:69], v[178:181], v[226:229], v[66:69]
	s_setprio 0
	s_barrier
	s_add_i32 s12, s16, s38
	v_lshl_add_u64 v[162:163], s[28:29], 0, v[64:65]
	s_mov_b32 m0, s12
	ds_read_b128 v[182:185], v145 offset:16384
	ds_read_b128 v[186:189], v145 offset:17408
	ds_read_b128 v[190:193], v145 offset:18432
	ds_read_b128 v[194:197], v145 offset:19456
	ds_read_b128 v[198:201], v145 offset:20480
	ds_read_b128 v[202:205], v145 offset:21504
	ds_read_b128 v[206:209], v145 offset:22528
	ds_read_b128 v[226:229], v145 offset:23552
	global_load_lds_dwordx4 v[162:163], off
	s_add_i32 m0, s12, 0x2000
	s_add_u32 s12, s28, 0x40000
	v_lshl_add_u64 v[210:211], s[28:29], 0, v[130:131]
	s_addc_u32 s13, s29, 0
	s_add_i32 s14, s14, s38
	global_load_lds_dwordx4 v[210:211], off
	v_lshl_add_u64 v[244:245], s[12:13], 0, v[64:65]
	s_mov_b32 m0, s14
	v_lshl_add_u64 v[212:213], s[36:37], 0, v[132:133]
	global_load_lds_dwordx4 v[244:245], off
	v_lshl_add_u64 v[244:245], s[12:13], 0, v[130:131]
	s_add_i32 m0, s14, 0x2000
	v_readlane_b32 s12, v251, 21
	global_load_lds_dwordx4 v[244:245], off
	v_lshl_add_u64 v[244:245], s[36:37], 0, v[134:135]
	s_mov_b32 m0, s25
	s_nop 0
	global_load_lds_dwordx4 v[244:245], off
	s_mov_b32 m0, s12
	s_nop 0
	global_load_lds_dwordx4 v[212:213], off
	s_waitcnt vmcnt(8)
	s_waitcnt lgkmcnt(0)
	s_barrier
	s_setprio 1
	s_waitcnt lgkmcnt(0)
	v_mfma_f32_16x16x32_bf16 v[60:63], v[146:149], v[182:185], v[60:63]
	v_mfma_f32_16x16x32_bf16 v[56:59], v[154:157], v[182:185], v[56:59]
	v_mfma_f32_16x16x32_bf16 v[44:47], v[146:149], v[190:193], v[44:47]
	v_mfma_f32_16x16x32_bf16 v[40:43], v[154:157], v[190:193], v[40:43]
	v_mfma_f32_16x16x32_bf16 v[28:31], v[146:149], v[198:201], v[28:31]
	v_mfma_f32_16x16x32_bf16 v[24:27], v[154:157], v[198:201], v[24:27]
	v_mfma_f32_16x16x32_bf16 v[12:15], v[146:149], v[206:209], v[12:15]
	v_mfma_f32_16x16x32_bf16 v[8:11], v[154:157], v[206:209], v[8:11]
	v_mfma_f32_16x16x32_bf16 v[60:63], v[150:153], v[186:189], v[60:63]
	v_mfma_f32_16x16x32_bf16 v[56:59], v[158:161], v[186:189], v[56:59]
	v_mfma_f32_16x16x32_bf16 v[44:47], v[150:153], v[194:197], v[44:47]
	v_mfma_f32_16x16x32_bf16 v[40:43], v[158:161], v[194:197], v[40:43]
	v_mfma_f32_16x16x32_bf16 v[28:31], v[150:153], v[202:205], v[28:31]
	v_mfma_f32_16x16x32_bf16 v[24:27], v[158:161], v[202:205], v[24:27]
	v_mfma_f32_16x16x32_bf16 v[12:15], v[150:153], v[226:229], v[12:15]
	v_mfma_f32_16x16x32_bf16 v[8:11], v[158:161], v[226:229], v[8:11]
	s_setprio 0
	s_setprio 1
	v_mfma_f32_16x16x32_bf16 v[52:55], v[166:169], v[182:185], v[52:55]
	v_mfma_f32_16x16x32_bf16 v[48:51], v[174:177], v[182:185], v[48:51]
	v_mfma_f32_16x16x32_bf16 v[36:39], v[166:169], v[190:193], v[36:39]
	v_mfma_f32_16x16x32_bf16 v[32:35], v[174:177], v[190:193], v[32:35]
	v_mfma_f32_16x16x32_bf16 v[20:23], v[166:169], v[198:201], v[20:23]
	v_mfma_f32_16x16x32_bf16 v[16:19], v[174:177], v[198:201], v[16:19]
	v_mfma_f32_16x16x32_bf16 v[4:7], v[166:169], v[206:209], v[4:7]
	v_mfma_f32_16x16x32_bf16 v[0:3], v[174:177], v[206:209], v[0:3]
	v_mfma_f32_16x16x32_bf16 v[52:55], v[170:173], v[186:189], v[52:55]
	v_mfma_f32_16x16x32_bf16 v[48:51], v[178:181], v[186:189], v[48:51]
	v_mfma_f32_16x16x32_bf16 v[36:39], v[170:173], v[194:197], v[36:39]
	v_mfma_f32_16x16x32_bf16 v[32:35], v[178:181], v[194:197], v[32:35]
	v_mfma_f32_16x16x32_bf16 v[20:23], v[170:173], v[202:205], v[20:23]
	v_mfma_f32_16x16x32_bf16 v[16:19], v[178:181], v[202:205], v[16:19]
	v_mfma_f32_16x16x32_bf16 v[4:7], v[170:173], v[226:229], v[4:7]
	v_mfma_f32_16x16x32_bf16 v[0:3], v[178:181], v[226:229], v[0:3]
	s_setprio 0
	s_barrier
	s_add_i32 s14, 0, 0x18000
	s_add_i32 s15, 0, 0x1c000
	v_add_u32_e32 v158, s14, v144
	v_add_u32_e32 v178, s15, v144
	ds_read_b128 v[146:149], v158
	ds_read_b128 v[150:153], v158 offset:1024
	ds_read_b128 v[154:157], v158 offset:2048
	ds_read_b128 v[158:161], v158 offset:3072
	ds_read_b128 v[166:169], v178
	ds_read_b128 v[170:173], v178 offset:1024
	ds_read_b128 v[174:177], v178 offset:2048
	ds_read_b128 v[178:181], v178 offset:3072
	s_add_u32 s12, s36, 0x40000
	s_addc_u32 s13, s37, 0
	s_mov_b32 m0, s75
	v_lshl_add_u64 v[218:219], s[12:13], 0, v[134:135]
	ds_read_b128 v[182:185], v145 offset:32768
	ds_read_b128 v[186:189], v145 offset:33792
	ds_read_b128 v[190:193], v145 offset:34816
	ds_read_b128 v[194:197], v145 offset:35840
	ds_read_b128 v[198:201], v145 offset:36864
	ds_read_b128 v[202:205], v145 offset:37888
	ds_read_b128 v[206:209], v145 offset:38912
	ds_read_b128 v[226:229], v145 offset:39936
	global_load_lds_dwordx4 v[218:219], off
	v_lshl_add_u64 v[218:219], s[12:13], 0, v[132:133]
	s_mov_b32 m0, s74
	s_nop 0
	global_load_lds_dwordx4 v[218:219], off
	s_waitcnt vmcnt(8)
	s_waitcnt lgkmcnt(0)
	s_barrier
	s_setprio 1
	s_waitcnt lgkmcnt(0)
	v_mfma_f32_16x16x32_bf16 v[126:129], v[146:149], v[182:185], v[126:129]
	v_mfma_f32_16x16x32_bf16 v[122:125], v[154:157], v[182:185], v[122:125]
	v_mfma_f32_16x16x32_bf16 v[110:113], v[146:149], v[190:193], v[110:113]
	v_mfma_f32_16x16x32_bf16 v[106:109], v[154:157], v[190:193], v[106:109]
	v_mfma_f32_16x16x32_bf16 v[94:97], v[146:149], v[198:201], v[94:97]
	v_mfma_f32_16x16x32_bf16 v[90:93], v[154:157], v[198:201], v[90:93]
	v_mfma_f32_16x16x32_bf16 v[78:81], v[146:149], v[206:209], v[78:81]
	v_mfma_f32_16x16x32_bf16 v[74:77], v[154:157], v[206:209], v[74:77]
	v_mfma_f32_16x16x32_bf16 v[126:129], v[150:153], v[186:189], v[126:129]
	v_mfma_f32_16x16x32_bf16 v[122:125], v[158:161], v[186:189], v[122:125]
	v_mfma_f32_16x16x32_bf16 v[110:113], v[150:153], v[194:197], v[110:113]
	v_mfma_f32_16x16x32_bf16 v[106:109], v[158:161], v[194:197], v[106:109]
	v_mfma_f32_16x16x32_bf16 v[94:97], v[150:153], v[202:205], v[94:97]
	v_mfma_f32_16x16x32_bf16 v[90:93], v[158:161], v[202:205], v[90:93]
	v_mfma_f32_16x16x32_bf16 v[78:81], v[150:153], v[226:229], v[78:81]
	v_mfma_f32_16x16x32_bf16 v[74:77], v[158:161], v[226:229], v[74:77]
	s_setprio 0
	s_setprio 1
	v_mfma_f32_16x16x32_bf16 v[118:121], v[166:169], v[182:185], v[118:121]
	v_mfma_f32_16x16x32_bf16 v[114:117], v[174:177], v[182:185], v[114:117]
	v_mfma_f32_16x16x32_bf16 v[102:105], v[166:169], v[190:193], v[102:105]
	v_mfma_f32_16x16x32_bf16 v[98:101], v[174:177], v[190:193], v[98:101]
	v_mfma_f32_16x16x32_bf16 v[86:89], v[166:169], v[198:201], v[86:89]
	v_mfma_f32_16x16x32_bf16 v[82:85], v[174:177], v[198:201], v[82:85]
	v_mfma_f32_16x16x32_bf16 v[70:73], v[166:169], v[206:209], v[70:73]
	v_mfma_f32_16x16x32_bf16 v[66:69], v[174:177], v[206:209], v[66:69]
	v_mfma_f32_16x16x32_bf16 v[118:121], v[170:173], v[186:189], v[118:121]
	v_mfma_f32_16x16x32_bf16 v[114:117], v[178:181], v[186:189], v[114:117]
	v_mfma_f32_16x16x32_bf16 v[102:105], v[170:173], v[194:197], v[102:105]
	v_mfma_f32_16x16x32_bf16 v[98:101], v[178:181], v[194:197], v[98:101]
	v_mfma_f32_16x16x32_bf16 v[86:89], v[170:173], v[202:205], v[86:89]
	v_mfma_f32_16x16x32_bf16 v[82:85], v[178:181], v[202:205], v[82:85]
	v_mfma_f32_16x16x32_bf16 v[70:73], v[170:173], v[226:229], v[70:73]
	v_mfma_f32_16x16x32_bf16 v[66:69], v[178:181], v[226:229], v[66:69]
	s_setprio 0
	s_barrier
	s_add_i32 s12, s14, s38
	v_lshl_add_u64 v[162:163], v[162:163], 0, s[40:41]
	s_mov_b32 m0, s12
	ds_read_b128 v[182:185], v145 offset:49152
	ds_read_b128 v[186:189], v145 offset:50176
	ds_read_b128 v[190:193], v145 offset:51200
	ds_read_b128 v[194:197], v145 offset:52224
	ds_read_b128 v[198:201], v145 offset:53248
	ds_read_b128 v[202:205], v145 offset:54272
	ds_read_b128 v[206:209], v145 offset:55296
	ds_read_b128 v[226:229], v145 offset:56320
	global_load_lds_dwordx4 v[162:163], off
	s_add_i32 m0, s12, 0x2000
	s_add_u32 s12, s28, 0x40080
	v_lshl_add_u64 v[162:163], v[210:211], 0, s[40:41]
	s_addc_u32 s13, s29, 0
	s_add_i32 s14, s15, s38
	global_load_lds_dwordx4 v[162:163], off
	v_lshl_add_u64 v[162:163], s[12:13], 0, v[64:65]
	s_mov_b32 m0, s14
	s_nop 0
	global_load_lds_dwordx4 v[162:163], off
	v_lshl_add_u64 v[162:163], s[12:13], 0, v[130:131]
	s_add_i32 m0, s14, 0x2000
	s_nop 0
	global_load_lds_dwordx4 v[162:163], off
	v_lshl_add_u64 v[162:163], v[244:245], 0, s[40:41]
	s_mov_b32 m0, s92
	s_nop 0
	global_load_lds_dwordx4 v[162:163], off
	v_lshl_add_u64 v[162:163], v[212:213], 0, s[40:41]
	s_mov_b32 m0, s78
	s_nop 0
	global_load_lds_dwordx4 v[162:163], off
	s_waitcnt vmcnt(8)
	s_waitcnt lgkmcnt(0)
	s_barrier
	s_setprio 1
	s_waitcnt lgkmcnt(0)
	v_mfma_f32_16x16x32_bf16 v[60:63], v[146:149], v[182:185], v[60:63]
	v_mfma_f32_16x16x32_bf16 v[56:59], v[154:157], v[182:185], v[56:59]
	v_mfma_f32_16x16x32_bf16 v[44:47], v[146:149], v[190:193], v[44:47]
	v_mfma_f32_16x16x32_bf16 v[40:43], v[154:157], v[190:193], v[40:43]
	v_mfma_f32_16x16x32_bf16 v[28:31], v[146:149], v[198:201], v[28:31]
	v_mfma_f32_16x16x32_bf16 v[24:27], v[154:157], v[198:201], v[24:27]
	v_mfma_f32_16x16x32_bf16 v[12:15], v[146:149], v[206:209], v[12:15]
	v_mfma_f32_16x16x32_bf16 v[8:11], v[154:157], v[206:209], v[8:11]
	v_mfma_f32_16x16x32_bf16 v[60:63], v[150:153], v[186:189], v[60:63]
	v_mfma_f32_16x16x32_bf16 v[56:59], v[158:161], v[186:189], v[56:59]
	v_mfma_f32_16x16x32_bf16 v[44:47], v[150:153], v[194:197], v[44:47]
	v_mfma_f32_16x16x32_bf16 v[40:43], v[158:161], v[194:197], v[40:43]
	v_mfma_f32_16x16x32_bf16 v[28:31], v[150:153], v[202:205], v[28:31]
	v_mfma_f32_16x16x32_bf16 v[24:27], v[158:161], v[202:205], v[24:27]
	v_mfma_f32_16x16x32_bf16 v[12:15], v[150:153], v[226:229], v[12:15]
	v_mfma_f32_16x16x32_bf16 v[8:11], v[158:161], v[226:229], v[8:11]
	s_setprio 0
	s_setprio 1
	v_mfma_f32_16x16x32_bf16 v[52:55], v[166:169], v[182:185], v[52:55]
	v_mfma_f32_16x16x32_bf16 v[48:51], v[174:177], v[182:185], v[48:51]
	v_mfma_f32_16x16x32_bf16 v[36:39], v[166:169], v[190:193], v[36:39]
	v_mfma_f32_16x16x32_bf16 v[32:35], v[174:177], v[190:193], v[32:35]
	v_mfma_f32_16x16x32_bf16 v[20:23], v[166:169], v[198:201], v[20:23]
	v_mfma_f32_16x16x32_bf16 v[16:19], v[174:177], v[198:201], v[16:19]
	v_mfma_f32_16x16x32_bf16 v[4:7], v[166:169], v[206:209], v[4:7]
	v_mfma_f32_16x16x32_bf16 v[0:3], v[174:177], v[206:209], v[0:3]
	v_mfma_f32_16x16x32_bf16 v[52:55], v[170:173], v[186:189], v[52:55]
	v_mfma_f32_16x16x32_bf16 v[48:51], v[178:181], v[186:189], v[48:51]
	v_mfma_f32_16x16x32_bf16 v[36:39], v[170:173], v[194:197], v[36:39]
	v_mfma_f32_16x16x32_bf16 v[32:35], v[178:181], v[194:197], v[32:35]
	v_mfma_f32_16x16x32_bf16 v[20:23], v[170:173], v[202:205], v[20:23]
	v_mfma_f32_16x16x32_bf16 v[16:19], v[178:181], v[202:205], v[16:19]
	v_mfma_f32_16x16x32_bf16 v[4:7], v[170:173], v[226:229], v[4:7]
	v_mfma_f32_16x16x32_bf16 v[0:3], v[178:181], v[226:229], v[0:3]
	s_setprio 0
	s_add_i32 s11, s11, 2
	s_add_u32 s52, s52, 0x100
	s_addc_u32 s53, s53, 0
	s_cmp_gt_u32 s11, 13
	s_barrier
	s_cbranch_scc0 .LBB0_51
	s_add_u32 s28, s5, 0xffffff00
	s_addc_u32 s29, s6, -1
	s_andn2_b64 vcc, exec, s[0:1]
	s_cbranch_vccnz .LBB0_54
	v_mov_b32_e32 v0, 0
	s_mov_b32 s2, s44
	s_mov_b32 s54, s46
	s_mov_b64 s[22:23], s[50:51]
	s_mov_b32 s56, s4
	v_mov_b32_e32 v1, v0
	v_mov_b32_e32 v2, v0
	v_mov_b32_e32 v3, v0
	v_mov_b32_e32 v4, v0
	v_mov_b32_e32 v5, v0
	v_mov_b32_e32 v6, v0
	v_mov_b32_e32 v7, v0
	v_mov_b32_e32 v16, v0
	v_mov_b32_e32 v17, v0
	v_mov_b32_e32 v18, v0
	v_mov_b32_e32 v19, v0
	v_mov_b32_e32 v20, v0
	v_mov_b32_e32 v21, v0
	v_mov_b32_e32 v22, v0
	v_mov_b32_e32 v23, v0
	v_mov_b32_e32 v32, v0
	v_mov_b32_e32 v33, v0
	v_mov_b32_e32 v34, v0
	v_mov_b32_e32 v35, v0
	v_mov_b32_e32 v36, v0
	v_mov_b32_e32 v37, v0
	v_mov_b32_e32 v38, v0
	v_mov_b32_e32 v39, v0
	v_mov_b32_e32 v48, v0
	v_mov_b32_e32 v49, v0
	v_mov_b32_e32 v50, v0
	v_mov_b32_e32 v51, v0
	v_mov_b32_e32 v52, v0
	v_mov_b32_e32 v53, v0
	v_mov_b32_e32 v54, v0
	v_mov_b32_e32 v55, v0
	v_mov_b32_e32 v8, v0
	v_mov_b32_e32 v9, v0
	v_mov_b32_e32 v10, v0
	v_mov_b32_e32 v11, v0
	v_mov_b32_e32 v12, v0
	v_mov_b32_e32 v13, v0
	v_mov_b32_e32 v14, v0
	v_mov_b32_e32 v15, v0
	v_mov_b32_e32 v24, v0
	v_mov_b32_e32 v25, v0
	v_mov_b32_e32 v26, v0
	v_mov_b32_e32 v27, v0
	v_mov_b32_e32 v28, v0
	v_mov_b32_e32 v29, v0
	v_mov_b32_e32 v30, v0
	v_mov_b32_e32 v31, v0
	v_mov_b32_e32 v40, v0
	v_mov_b32_e32 v41, v0
	v_mov_b32_e32 v42, v0
	v_mov_b32_e32 v43, v0
	v_mov_b32_e32 v44, v0
	v_mov_b32_e32 v45, v0
	v_mov_b32_e32 v46, v0
	v_mov_b32_e32 v47, v0
	v_mov_b32_e32 v56, v0
	v_mov_b32_e32 v57, v0
	v_mov_b32_e32 v58, v0
	v_mov_b32_e32 v59, v0
	v_mov_b32_e32 v60, v0
	v_mov_b32_e32 v61, v0
	v_mov_b32_e32 v62, v0
	v_mov_b32_e32 v63, v0
	v_mov_b32_e32 v66, v0
	v_mov_b32_e32 v67, v0
	v_mov_b32_e32 v68, v0
	v_mov_b32_e32 v69, v0
	v_mov_b32_e32 v70, v0
	v_mov_b32_e32 v71, v0
	v_mov_b32_e32 v72, v0
	v_mov_b32_e32 v73, v0
	v_mov_b32_e32 v82, v0
	v_mov_b32_e32 v83, v0
	v_mov_b32_e32 v84, v0
	v_mov_b32_e32 v85, v0
	v_mov_b32_e32 v86, v0
	v_mov_b32_e32 v87, v0
	v_mov_b32_e32 v88, v0
	v_mov_b32_e32 v89, v0
	v_mov_b32_e32 v98, v0
	v_mov_b32_e32 v99, v0
	v_mov_b32_e32 v100, v0
	v_mov_b32_e32 v101, v0
	v_mov_b32_e32 v102, v0
	v_mov_b32_e32 v103, v0
	v_mov_b32_e32 v104, v0
	v_mov_b32_e32 v105, v0
	v_mov_b32_e32 v114, v0
	v_mov_b32_e32 v115, v0
	v_mov_b32_e32 v116, v0
	v_mov_b32_e32 v117, v0
	v_mov_b32_e32 v118, v0
	v_mov_b32_e32 v119, v0
	v_mov_b32_e32 v120, v0
	v_mov_b32_e32 v121, v0
	v_mov_b32_e32 v74, v0
	v_mov_b32_e32 v75, v0
	v_mov_b32_e32 v76, v0
	v_mov_b32_e32 v77, v0
	v_mov_b32_e32 v78, v0
	v_mov_b32_e32 v79, v0
	v_mov_b32_e32 v80, v0
	v_mov_b32_e32 v81, v0
	v_mov_b32_e32 v90, v0
	v_mov_b32_e32 v91, v0
	v_mov_b32_e32 v92, v0
	v_mov_b32_e32 v93, v0
	v_mov_b32_e32 v94, v0
	v_mov_b32_e32 v95, v0
	v_mov_b32_e32 v96, v0
	v_mov_b32_e32 v97, v0
	v_mov_b32_e32 v106, v0
	v_mov_b32_e32 v107, v0
	v_mov_b32_e32 v108, v0
	v_mov_b32_e32 v109, v0
	v_mov_b32_e32 v110, v0
	v_mov_b32_e32 v111, v0
	v_mov_b32_e32 v112, v0
	v_mov_b32_e32 v113, v0
	v_mov_b32_e32 v122, v0
	v_mov_b32_e32 v123, v0
	v_mov_b32_e32 v124, v0
	v_mov_b32_e32 v125, v0
	v_mov_b32_e32 v126, v0
	v_mov_b32_e32 v127, v0
	v_mov_b32_e32 v128, v0
	v_mov_b32_e32 v129, v0
	s_andn2_b64 vcc, exec, s[42:43]
	s_cbranch_vccnz .LBB0_55
	s_branch .LBB0_56

.LBB0_572:
	v_add_u32_e32 v146, 0x10000, v104
	ds_read_b128 v[150:153], v146
	ds_read_b128 v[154:157], v146 offset:1024
	ds_read_b128 v[158:161], v146 offset:2048
	ds_read_b128 v[162:165], v146 offset:3072
	v_add_u32_e32 v146, 0x14000, v104
	ds_read_b128 v[166:169], v146
	ds_read_b128 v[170:173], v146 offset:1024
	ds_read_b128 v[174:177], v146 offset:2048
	ds_read_b128 v[178:181], v146 offset:3072
	s_add_u32 s12, s22, s52
	s_addc_u32 s13, s23, s53
	s_add_u32 s12, s12, 0x100
	s_addc_u32 s13, s13, 0
	s_add_u32 s14, s5, s52
	s_addc_u32 s15, s6, s53
	s_add_i32 s16, 0, 0x10000
	s_cmpk_eq_i32 s52, 0x1f00
	s_cselect_b32 s37, s7, s13
	s_cselect_b32 s36, s8, s12
	s_cselect_b32 s29, s9, s15
	s_cselect_b32 s28, s10, s14
	s_add_i32 s14, 0, 0x14000
	s_mov_b32 m0, s80
	v_lshl_add_u64 v[146:147], v[100:101], 0, s[52:53]
	ds_read_b128 v[182:185], v105
	ds_read_b128 v[186:189], v105 offset:1024
	ds_read_b128 v[190:193], v105 offset:2048
	ds_read_b128 v[194:197], v105 offset:3072
	ds_read_b128 v[198:201], v105 offset:4096
	ds_read_b128 v[202:205], v105 offset:5120
	ds_read_b128 v[206:209], v105 offset:6144
	ds_read_b128 v[226:229], v105 offset:7168
	global_load_lds_dwordx4 v[146:147], off
	v_lshl_add_u64 v[146:147], v[102:103], 0, s[52:53]
	s_add_i32 m0, s25, 0xe000
	s_nop 0
	global_load_lds_dwordx4 v[146:147], off
	s_waitcnt vmcnt(8)
	s_waitcnt lgkmcnt(0)
	s_barrier
	s_setprio 1
	s_waitcnt lgkmcnt(0)
	v_mfma_f32_16x16x32_bf16 v[134:137], v[150:153], v[182:185], v[134:137]
	v_mfma_f32_16x16x32_bf16 v[142:145], v[158:161], v[182:185], v[142:145]
	v_mfma_f32_16x16x32_bf16 v[126:129], v[150:153], v[190:193], v[126:129]
	v_mfma_f32_16x16x32_bf16 v[122:125], v[158:161], v[190:193], v[122:125]
	v_mfma_f32_16x16x32_bf16 v[110:113], v[150:153], v[198:201], v[110:113]
	v_mfma_f32_16x16x32_bf16 v[106:109], v[158:161], v[198:201], v[106:109]
	v_mfma_f32_16x16x32_bf16 v[78:81], v[150:153], v[206:209], v[78:81]
	v_mfma_f32_16x16x32_bf16 v[74:77], v[158:161], v[206:209], v[74:77]
	v_mfma_f32_16x16x32_bf16 v[134:137], v[154:157], v[186:189], v[134:137]
	v_mfma_f32_16x16x32_bf16 v[142:145], v[162:165], v[186:189], v[142:145]
	v_mfma_f32_16x16x32_bf16 v[126:129], v[154:157], v[194:197], v[126:129]
	v_mfma_f32_16x16x32_bf16 v[122:125], v[162:165], v[194:197], v[122:125]
	v_mfma_f32_16x16x32_bf16 v[110:113], v[154:157], v[202:205], v[110:113]
	v_mfma_f32_16x16x32_bf16 v[106:109], v[162:165], v[202:205], v[106:109]
	v_mfma_f32_16x16x32_bf16 v[78:81], v[154:157], v[226:229], v[78:81]
	v_mfma_f32_16x16x32_bf16 v[74:77], v[162:165], v[226:229], v[74:77]
	s_setprio 0
	s_setprio 1
	v_mfma_f32_16x16x32_bf16 v[138:141], v[166:169], v[182:185], v[138:141]
	v_mfma_f32_16x16x32_bf16 v[130:133], v[174:177], v[182:185], v[130:133]
	v_mfma_f32_16x16x32_bf16 v[118:121], v[166:169], v[190:193], v[118:121]
	v_mfma_f32_16x16x32_bf16 v[114:117], v[174:177], v[190:193], v[114:117]
	v_mfma_f32_16x16x32_bf16 v[94:97], v[166:169], v[198:201], v[94:97]
	v_mfma_f32_16x16x32_bf16 v[86:89], v[174:177], v[198:201], v[86:89]
	v_mfma_f32_16x16x32_bf16 v[70:73], v[166:169], v[206:209], v[70:73]
	v_mfma_f32_16x16x32_bf16 v[66:69], v[174:177], v[206:209], v[66:69]
	v_mfma_f32_16x16x32_bf16 v[138:141], v[170:173], v[186:189], v[138:141]
	v_mfma_f32_16x16x32_bf16 v[130:133], v[178:181], v[186:189], v[130:133]
	v_mfma_f32_16x16x32_bf16 v[118:121], v[170:173], v[194:197], v[118:121]
	v_mfma_f32_16x16x32_bf16 v[114:117], v[178:181], v[194:197], v[114:117]
	v_mfma_f32_16x16x32_bf16 v[94:97], v[170:173], v[202:205], v[94:97]
	v_mfma_f32_16x16x32_bf16 v[86:89], v[178:181], v[202:205], v[86:89]
	v_mfma_f32_16x16x32_bf16 v[70:73], v[170:173], v[226:229], v[70:73]
	v_mfma_f32_16x16x32_bf16 v[66:69], v[178:181], v[226:229], v[66:69]
	s_setprio 0
	s_barrier
	s_add_i32 s12, s16, s38
	v_lshl_add_u64 v[146:147], s[28:29], 0, v[64:65]
	s_mov_b32 m0, s12
	ds_read_b128 v[182:185], v105 offset:16384
	ds_read_b128 v[186:189], v105 offset:17408
	ds_read_b128 v[190:193], v105 offset:18432
	ds_read_b128 v[194:197], v105 offset:19456
	ds_read_b128 v[198:201], v105 offset:20480
	ds_read_b128 v[202:205], v105 offset:21504
	ds_read_b128 v[206:209], v105 offset:22528
	ds_read_b128 v[226:229], v105 offset:23552
	global_load_lds_dwordx4 v[146:147], off
	s_add_i32 m0, s12, 0x2000
	s_add_u32 s12, s28, 0x100000
	v_lshl_add_u64 v[210:211], s[28:29], 0, v[82:83]
	s_addc_u32 s13, s29, 0
	s_add_i32 s14, s14, s38
	global_load_lds_dwordx4 v[210:211], off
	v_lshl_add_u64 v[212:213], s[12:13], 0, v[64:65]
	s_mov_b32 m0, s14
	v_lshl_add_u64 v[218:219], s[36:37], 0, v[84:85]
	global_load_lds_dwordx4 v[212:213], off
	v_lshl_add_u64 v[212:213], s[12:13], 0, v[82:83]
	s_add_i32 m0, s14, 0x2000
	v_readlane_b32 s12, v251, 21
	global_load_lds_dwordx4 v[212:213], off
	v_lshl_add_u64 v[212:213], s[36:37], 0, v[90:91]
	s_mov_b32 m0, s25
	s_nop 0
	global_load_lds_dwordx4 v[212:213], off
	s_mov_b32 m0, s12
	s_nop 0
	global_load_lds_dwordx4 v[218:219], off
	s_waitcnt vmcnt(8)
	s_waitcnt lgkmcnt(0)
	s_barrier
	s_setprio 1
	s_waitcnt lgkmcnt(0)
	v_mfma_f32_16x16x32_bf16 v[60:63], v[150:153], v[182:185], v[60:63]
	v_mfma_f32_16x16x32_bf16 v[56:59], v[158:161], v[182:185], v[56:59]
	v_mfma_f32_16x16x32_bf16 v[44:47], v[150:153], v[190:193], v[44:47]
	v_mfma_f32_16x16x32_bf16 v[40:43], v[158:161], v[190:193], v[40:43]
	v_mfma_f32_16x16x32_bf16 v[28:31], v[150:153], v[198:201], v[28:31]
	v_mfma_f32_16x16x32_bf16 v[24:27], v[158:161], v[198:201], v[24:27]
	v_mfma_f32_16x16x32_bf16 v[12:15], v[150:153], v[206:209], v[12:15]
	v_mfma_f32_16x16x32_bf16 v[8:11], v[158:161], v[206:209], v[8:11]
	v_mfma_f32_16x16x32_bf16 v[60:63], v[154:157], v[186:189], v[60:63]
	v_mfma_f32_16x16x32_bf16 v[56:59], v[162:165], v[186:189], v[56:59]
	v_mfma_f32_16x16x32_bf16 v[44:47], v[154:157], v[194:197], v[44:47]
	v_mfma_f32_16x16x32_bf16 v[40:43], v[162:165], v[194:197], v[40:43]
	v_mfma_f32_16x16x32_bf16 v[28:31], v[154:157], v[202:205], v[28:31]
	v_mfma_f32_16x16x32_bf16 v[24:27], v[162:165], v[202:205], v[24:27]
	v_mfma_f32_16x16x32_bf16 v[12:15], v[154:157], v[226:229], v[12:15]
	v_mfma_f32_16x16x32_bf16 v[8:11], v[162:165], v[226:229], v[8:11]
	s_setprio 0
	s_setprio 1
	v_mfma_f32_16x16x32_bf16 v[52:55], v[166:169], v[182:185], v[52:55]
	v_mfma_f32_16x16x32_bf16 v[48:51], v[174:177], v[182:185], v[48:51]
	v_mfma_f32_16x16x32_bf16 v[36:39], v[166:169], v[190:193], v[36:39]
	v_mfma_f32_16x16x32_bf16 v[32:35], v[174:177], v[190:193], v[32:35]
	v_mfma_f32_16x16x32_bf16 v[20:23], v[166:169], v[198:201], v[20:23]
	v_mfma_f32_16x16x32_bf16 v[16:19], v[174:177], v[198:201], v[16:19]
	v_mfma_f32_16x16x32_bf16 v[4:7], v[166:169], v[206:209], v[4:7]
	v_mfma_f32_16x16x32_bf16 v[0:3], v[174:177], v[206:209], v[0:3]
	v_mfma_f32_16x16x32_bf16 v[52:55], v[170:173], v[186:189], v[52:55]
	v_mfma_f32_16x16x32_bf16 v[48:51], v[178:181], v[186:189], v[48:51]
	v_mfma_f32_16x16x32_bf16 v[36:39], v[170:173], v[194:197], v[36:39]
	v_mfma_f32_16x16x32_bf16 v[32:35], v[178:181], v[194:197], v[32:35]
	v_mfma_f32_16x16x32_bf16 v[20:23], v[170:173], v[202:205], v[20:23]
	v_mfma_f32_16x16x32_bf16 v[16:19], v[178:181], v[202:205], v[16:19]
	v_mfma_f32_16x16x32_bf16 v[4:7], v[170:173], v[226:229], v[4:7]
	v_mfma_f32_16x16x32_bf16 v[0:3], v[178:181], v[226:229], v[0:3]
	s_setprio 0
	s_barrier
	s_add_i32 s14, 0, 0x18000
	s_add_i32 s15, 0, 0x1c000
	v_add_u32_e32 v162, s14, v104
	v_add_u32_e32 v178, s15, v104
	ds_read_b128 v[150:153], v162
	ds_read_b128 v[154:157], v162 offset:1024
	ds_read_b128 v[158:161], v162 offset:2048
	ds_read_b128 v[162:165], v162 offset:3072
	ds_read_b128 v[166:169], v178
	ds_read_b128 v[170:173], v178 offset:1024
	ds_read_b128 v[174:177], v178 offset:2048
	ds_read_b128 v[178:181], v178 offset:3072
	s_add_u32 s12, s36, 0x100000
	s_addc_u32 s13, s37, 0
	s_mov_b32 m0, s75
	v_lshl_add_u64 v[230:231], s[12:13], 0, v[90:91]
	ds_read_b128 v[182:185], v105 offset:32768
	ds_read_b128 v[186:189], v105 offset:33792
	ds_read_b128 v[190:193], v105 offset:34816
	ds_read_b128 v[194:197], v105 offset:35840
	ds_read_b128 v[198:201], v105 offset:36864
	ds_read_b128 v[202:205], v105 offset:37888
	ds_read_b128 v[206:209], v105 offset:38912
	ds_read_b128 v[226:229], v105 offset:39936
	global_load_lds_dwordx4 v[230:231], off
	v_lshl_add_u64 v[230:231], s[12:13], 0, v[84:85]
	s_mov_b32 m0, s74
	s_nop 0
	global_load_lds_dwordx4 v[230:231], off
	s_waitcnt vmcnt(8)
	s_waitcnt lgkmcnt(0)
	s_barrier
	s_setprio 1
	s_waitcnt lgkmcnt(0)
	v_mfma_f32_16x16x32_bf16 v[134:137], v[150:153], v[182:185], v[134:137]
	v_mfma_f32_16x16x32_bf16 v[142:145], v[158:161], v[182:185], v[142:145]
	v_mfma_f32_16x16x32_bf16 v[126:129], v[150:153], v[190:193], v[126:129]
	v_mfma_f32_16x16x32_bf16 v[122:125], v[158:161], v[190:193], v[122:125]
	v_mfma_f32_16x16x32_bf16 v[110:113], v[150:153], v[198:201], v[110:113]
	v_mfma_f32_16x16x32_bf16 v[106:109], v[158:161], v[198:201], v[106:109]
	v_mfma_f32_16x16x32_bf16 v[78:81], v[150:153], v[206:209], v[78:81]
	v_mfma_f32_16x16x32_bf16 v[74:77], v[158:161], v[206:209], v[74:77]
	v_mfma_f32_16x16x32_bf16 v[134:137], v[154:157], v[186:189], v[134:137]
	v_mfma_f32_16x16x32_bf16 v[142:145], v[162:165], v[186:189], v[142:145]
	v_mfma_f32_16x16x32_bf16 v[126:129], v[154:157], v[194:197], v[126:129]
	v_mfma_f32_16x16x32_bf16 v[122:125], v[162:165], v[194:197], v[122:125]
	v_mfma_f32_16x16x32_bf16 v[110:113], v[154:157], v[202:205], v[110:113]
	v_mfma_f32_16x16x32_bf16 v[106:109], v[162:165], v[202:205], v[106:109]
	v_mfma_f32_16x16x32_bf16 v[78:81], v[154:157], v[226:229], v[78:81]
	v_mfma_f32_16x16x32_bf16 v[74:77], v[162:165], v[226:229], v[74:77]
	s_setprio 0
	s_setprio 1
	v_mfma_f32_16x16x32_bf16 v[138:141], v[166:169], v[182:185], v[138:141]
	v_mfma_f32_16x16x32_bf16 v[130:133], v[174:177], v[182:185], v[130:133]
	v_mfma_f32_16x16x32_bf16 v[118:121], v[166:169], v[190:193], v[118:121]
	v_mfma_f32_16x16x32_bf16 v[114:117], v[174:177], v[190:193], v[114:117]
	v_mfma_f32_16x16x32_bf16 v[94:97], v[166:169], v[198:201], v[94:97]
	v_mfma_f32_16x16x32_bf16 v[86:89], v[174:177], v[198:201], v[86:89]
	v_mfma_f32_16x16x32_bf16 v[70:73], v[166:169], v[206:209], v[70:73]
	v_mfma_f32_16x16x32_bf16 v[66:69], v[174:177], v[206:209], v[66:69]
	v_mfma_f32_16x16x32_bf16 v[138:141], v[170:173], v[186:189], v[138:141]
	v_mfma_f32_16x16x32_bf16 v[130:133], v[178:181], v[186:189], v[130:133]
	v_mfma_f32_16x16x32_bf16 v[118:121], v[170:173], v[194:197], v[118:121]
	v_mfma_f32_16x16x32_bf16 v[114:117], v[178:181], v[194:197], v[114:117]
	v_mfma_f32_16x16x32_bf16 v[94:97], v[170:173], v[202:205], v[94:97]
	v_mfma_f32_16x16x32_bf16 v[86:89], v[178:181], v[202:205], v[86:89]
	v_mfma_f32_16x16x32_bf16 v[70:73], v[170:173], v[226:229], v[70:73]
	v_mfma_f32_16x16x32_bf16 v[66:69], v[178:181], v[226:229], v[66:69]
	s_setprio 0
	s_barrier
	s_add_i32 s12, s14, s38
	v_lshl_add_u64 v[146:147], v[146:147], 0, s[18:19]
	s_mov_b32 m0, s12
	ds_read_b128 v[182:185], v105 offset:49152
	ds_read_b128 v[186:189], v105 offset:50176
	ds_read_b128 v[190:193], v105 offset:51200
	ds_read_b128 v[194:197], v105 offset:52224
	ds_read_b128 v[198:201], v105 offset:53248
	ds_read_b128 v[202:205], v105 offset:54272
	ds_read_b128 v[206:209], v105 offset:55296
	ds_read_b128 v[226:229], v105 offset:56320
	global_load_lds_dwordx4 v[146:147], off
	s_add_i32 m0, s12, 0x2000
	s_add_u32 s12, s28, 0x100080
	v_lshl_add_u64 v[146:147], v[210:211], 0, s[18:19]
	s_addc_u32 s13, s29, 0
	s_add_i32 s14, s15, s38
	global_load_lds_dwordx4 v[146:147], off
	v_lshl_add_u64 v[146:147], s[12:13], 0, v[64:65]
	s_mov_b32 m0, s14
	s_nop 0
	global_load_lds_dwordx4 v[146:147], off
	v_lshl_add_u64 v[146:147], s[12:13], 0, v[82:83]
	s_add_i32 m0, s14, 0x2000
	s_nop 0
	global_load_lds_dwordx4 v[146:147], off
	v_lshl_add_u64 v[146:147], v[212:213], 0, s[18:19]
	s_mov_b32 m0, s92
	s_nop 0
	global_load_lds_dwordx4 v[146:147], off
	v_lshl_add_u64 v[146:147], v[218:219], 0, s[18:19]
	s_mov_b32 m0, s78
	s_nop 0
	global_load_lds_dwordx4 v[146:147], off
	s_waitcnt vmcnt(8)
	s_waitcnt lgkmcnt(0)
	s_barrier
	s_setprio 1
	s_waitcnt lgkmcnt(0)
	v_mfma_f32_16x16x32_bf16 v[60:63], v[150:153], v[182:185], v[60:63]
	v_mfma_f32_16x16x32_bf16 v[56:59], v[158:161], v[182:185], v[56:59]
	v_mfma_f32_16x16x32_bf16 v[44:47], v[150:153], v[190:193], v[44:47]
	v_mfma_f32_16x16x32_bf16 v[40:43], v[158:161], v[190:193], v[40:43]
	v_mfma_f32_16x16x32_bf16 v[28:31], v[150:153], v[198:201], v[28:31]
	v_mfma_f32_16x16x32_bf16 v[24:27], v[158:161], v[198:201], v[24:27]
	v_mfma_f32_16x16x32_bf16 v[12:15], v[150:153], v[206:209], v[12:15]
	v_mfma_f32_16x16x32_bf16 v[8:11], v[158:161], v[206:209], v[8:11]
	v_mfma_f32_16x16x32_bf16 v[60:63], v[154:157], v[186:189], v[60:63]
	v_mfma_f32_16x16x32_bf16 v[56:59], v[162:165], v[186:189], v[56:59]
	v_mfma_f32_16x16x32_bf16 v[44:47], v[154:157], v[194:197], v[44:47]
	v_mfma_f32_16x16x32_bf16 v[40:43], v[162:165], v[194:197], v[40:43]
	v_mfma_f32_16x16x32_bf16 v[28:31], v[154:157], v[202:205], v[28:31]
	v_mfma_f32_16x16x32_bf16 v[24:27], v[162:165], v[202:205], v[24:27]
	v_mfma_f32_16x16x32_bf16 v[12:15], v[154:157], v[226:229], v[12:15]
	v_mfma_f32_16x16x32_bf16 v[8:11], v[162:165], v[226:229], v[8:11]
	s_setprio 0
	s_setprio 1
	v_mfma_f32_16x16x32_bf16 v[52:55], v[166:169], v[182:185], v[52:55]
	v_mfma_f32_16x16x32_bf16 v[48:51], v[174:177], v[182:185], v[48:51]
	v_mfma_f32_16x16x32_bf16 v[36:39], v[166:169], v[190:193], v[36:39]
	v_mfma_f32_16x16x32_bf16 v[32:35], v[174:177], v[190:193], v[32:35]
	v_mfma_f32_16x16x32_bf16 v[20:23], v[166:169], v[198:201], v[20:23]
	v_mfma_f32_16x16x32_bf16 v[16:19], v[174:177], v[198:201], v[16:19]
	v_mfma_f32_16x16x32_bf16 v[4:7], v[166:169], v[206:209], v[4:7]
	v_mfma_f32_16x16x32_bf16 v[0:3], v[174:177], v[206:209], v[0:3]
	v_mfma_f32_16x16x32_bf16 v[52:55], v[170:173], v[186:189], v[52:55]
	v_mfma_f32_16x16x32_bf16 v[48:51], v[178:181], v[186:189], v[48:51]
	v_mfma_f32_16x16x32_bf16 v[36:39], v[170:173], v[194:197], v[36:39]
	v_mfma_f32_16x16x32_bf16 v[32:35], v[178:181], v[194:197], v[32:35]
	v_mfma_f32_16x16x32_bf16 v[20:23], v[170:173], v[202:205], v[20:23]
	v_mfma_f32_16x16x32_bf16 v[16:19], v[178:181], v[202:205], v[16:19]
	v_mfma_f32_16x16x32_bf16 v[4:7], v[170:173], v[226:229], v[4:7]
	v_mfma_f32_16x16x32_bf16 v[0:3], v[178:181], v[226:229], v[0:3]
	s_setprio 0
	s_add_i32 s11, s11, 2
	s_add_u32 s52, s52, 0x100
	s_addc_u32 s53, s53, 0
	s_cmp_gt_u32 s11, 61
	s_barrier
	s_cbranch_scc0 .LBB0_572
	s_add_u32 s28, s5, 0xffffff00
	s_addc_u32 s29, s6, -1
	s_andn2_b64 vcc, exec, s[0:1]
	s_cbranch_vccnz .LBB0_575
	v_mov_b32_e32 v0, 0
	s_mov_b32 s40, s44
	s_mov_b32 s67, s46
	s_mov_b64 s[22:23], s[50:51]
	s_mov_b32 s56, s4
	v_mov_b32_e32 v1, v0
	v_mov_b32_e32 v2, v0
	v_mov_b32_e32 v3, v0
	v_mov_b32_e32 v4, v0
	v_mov_b32_e32 v5, v0
	v_mov_b32_e32 v6, v0
	v_mov_b32_e32 v7, v0
	v_mov_b32_e32 v16, v0
	v_mov_b32_e32 v17, v0
	v_mov_b32_e32 v18, v0
	v_mov_b32_e32 v19, v0
	v_mov_b32_e32 v20, v0
	v_mov_b32_e32 v21, v0
	v_mov_b32_e32 v22, v0
	v_mov_b32_e32 v23, v0
	v_mov_b32_e32 v32, v0
	v_mov_b32_e32 v33, v0
	v_mov_b32_e32 v34, v0
	v_mov_b32_e32 v35, v0
	v_mov_b32_e32 v36, v0
	v_mov_b32_e32 v37, v0
	v_mov_b32_e32 v38, v0
	v_mov_b32_e32 v39, v0
	v_mov_b32_e32 v48, v0
	v_mov_b32_e32 v49, v0
	v_mov_b32_e32 v50, v0
	v_mov_b32_e32 v51, v0
	v_mov_b32_e32 v52, v0
	v_mov_b32_e32 v53, v0
	v_mov_b32_e32 v54, v0
	v_mov_b32_e32 v55, v0
	v_mov_b32_e32 v8, v0
	v_mov_b32_e32 v9, v0
	v_mov_b32_e32 v10, v0
	v_mov_b32_e32 v11, v0
	v_mov_b32_e32 v12, v0
	v_mov_b32_e32 v13, v0
	v_mov_b32_e32 v14, v0
	v_mov_b32_e32 v15, v0
	v_mov_b32_e32 v24, v0
	v_mov_b32_e32 v25, v0
	v_mov_b32_e32 v26, v0
	v_mov_b32_e32 v27, v0
	v_mov_b32_e32 v28, v0
	v_mov_b32_e32 v29, v0
	v_mov_b32_e32 v30, v0
	v_mov_b32_e32 v31, v0
	v_mov_b32_e32 v40, v0
	v_mov_b32_e32 v41, v0
	v_mov_b32_e32 v42, v0
	v_mov_b32_e32 v43, v0
	v_mov_b32_e32 v44, v0
	v_mov_b32_e32 v45, v0
	v_mov_b32_e32 v46, v0
	v_mov_b32_e32 v47, v0
	v_mov_b32_e32 v56, v0
	v_mov_b32_e32 v57, v0
	v_mov_b32_e32 v58, v0
	v_mov_b32_e32 v59, v0
	v_mov_b32_e32 v60, v0
	v_mov_b32_e32 v61, v0
	v_mov_b32_e32 v62, v0
	v_mov_b32_e32 v63, v0
	v_mov_b32_e32 v66, v0
	v_mov_b32_e32 v67, v0
	v_mov_b32_e32 v68, v0
	v_mov_b32_e32 v69, v0
	v_mov_b32_e32 v70, v0
	v_mov_b32_e32 v71, v0
	v_mov_b32_e32 v72, v0
	v_mov_b32_e32 v73, v0
	v_mov_b32_e32 v86, v0
	v_mov_b32_e32 v87, v0
	v_mov_b32_e32 v88, v0
	v_mov_b32_e32 v89, v0
	v_mov_b32_e32 v94, v0
	v_mov_b32_e32 v95, v0
	v_mov_b32_e32 v96, v0
	v_mov_b32_e32 v97, v0
	v_mov_b32_e32 v114, v0
	v_mov_b32_e32 v115, v0
	v_mov_b32_e32 v116, v0
	v_mov_b32_e32 v117, v0
	v_mov_b32_e32 v118, v0
	v_mov_b32_e32 v119, v0
	v_mov_b32_e32 v120, v0
	v_mov_b32_e32 v121, v0
	v_mov_b32_e32 v130, v0
	v_mov_b32_e32 v131, v0
	v_mov_b32_e32 v132, v0
	v_mov_b32_e32 v133, v0
	v_mov_b32_e32 v138, v0
	v_mov_b32_e32 v139, v0
	v_mov_b32_e32 v140, v0
	v_mov_b32_e32 v141, v0
	v_mov_b32_e32 v74, v0
	v_mov_b32_e32 v75, v0
	v_mov_b32_e32 v76, v0
	v_mov_b32_e32 v77, v0
	v_mov_b32_e32 v78, v0
	v_mov_b32_e32 v79, v0
	v_mov_b32_e32 v80, v0
	v_mov_b32_e32 v81, v0
	v_mov_b32_e32 v106, v0
	v_mov_b32_e32 v107, v0
	v_mov_b32_e32 v108, v0
	v_mov_b32_e32 v109, v0
	v_mov_b32_e32 v110, v0
	v_mov_b32_e32 v111, v0
	v_mov_b32_e32 v112, v0
	v_mov_b32_e32 v113, v0
	v_mov_b32_e32 v122, v0
	v_mov_b32_e32 v123, v0
	v_mov_b32_e32 v124, v0
	v_mov_b32_e32 v125, v0
	v_mov_b32_e32 v126, v0
	v_mov_b32_e32 v127, v0
	v_mov_b32_e32 v128, v0
	v_mov_b32_e32 v129, v0
	v_mov_b32_e32 v142, v0
	v_mov_b32_e32 v143, v0
	v_mov_b32_e32 v144, v0
	v_mov_b32_e32 v145, v0
	v_mov_b32_e32 v134, v0
	v_mov_b32_e32 v135, v0
	v_mov_b32_e32 v136, v0
	v_mov_b32_e32 v137, v0
	s_andn2_b64 vcc, exec, s[42:43]
	s_cbranch_vccnz .LBB0_576
	s_branch .LBB0_577

.LBB0_789:
	v_add_u32_e32 v142, 0x10000, v181
	v_add_u32_e32 v168, 0x14000, v181
	ds_read_b128 v[130:133], v142
	ds_read_b128 v[134:137], v142 offset:1024
	ds_read_b128 v[138:141], v142 offset:2048
	ds_read_b128 v[142:145], v142 offset:3072
	ds_read_b128 v[146:149], v168
	ds_read_b128 v[160:163], v168 offset:1024
	ds_read_b128 v[164:167], v168 offset:2048
	ds_read_b128 v[168:171], v168 offset:3072
	s_add_u32 s10, s52, 0xfffc0080
	s_addc_u32 s11, s53, -1
	s_add_i32 s12, 0, 0x10000
	s_cmp_eq_u32 s9, 12
	s_cselect_b32 s37, s1, s11
	s_cselect_b32 s36, s4, s10
	s_cselect_b32 s29, s5, s8
	s_cselect_b32 s28, s6, s7
	s_add_i32 s13, 0, 0x14000
	s_mov_b32 m0, s80
	v_lshl_add_u64 v[176:177], s[52:53], 0, v[156:157]
	ds_read_b128 v[172:175], v184
	ds_read_b128 v[186:189], v184 offset:1024
	ds_read_b128 v[190:193], v184 offset:2048
	ds_read_b128 v[194:197], v184 offset:3072
	ds_read_b128 v[198:201], v184 offset:4096
	ds_read_b128 v[202:205], v184 offset:5120
	ds_read_b128 v[206:209], v184 offset:6144
	ds_read_b128 v[226:229], v184 offset:7168
	global_load_lds_dwordx4 v[176:177], off
	v_lshl_add_u64 v[176:177], s[52:53], 0, v[158:159]
	s_add_i32 m0, s25, 0xe000
	s_nop 0
	global_load_lds_dwordx4 v[176:177], off
	s_waitcnt vmcnt(8)
	s_waitcnt lgkmcnt(0)
	s_barrier
	s_setprio 1
	s_waitcnt lgkmcnt(0)
	v_mfma_f32_16x16x32_bf16 v[126:129], v[130:133], v[172:175], v[126:129]
	v_mfma_f32_16x16x32_bf16 v[122:125], v[138:141], v[172:175], v[122:125]
	v_mfma_f32_16x16x32_bf16 v[114:117], v[130:133], v[190:193], v[114:117]
	v_mfma_f32_16x16x32_bf16 v[106:109], v[138:141], v[190:193], v[106:109]
	v_mfma_f32_16x16x32_bf16 v[98:101], v[130:133], v[198:201], v[98:101]
	v_mfma_f32_16x16x32_bf16 v[90:93], v[138:141], v[198:201], v[90:93]
	v_mfma_f32_16x16x32_bf16 v[82:85], v[130:133], v[206:209], v[82:85]
	v_mfma_f32_16x16x32_bf16 v[74:77], v[138:141], v[206:209], v[74:77]
	v_mfma_f32_16x16x32_bf16 v[126:129], v[134:137], v[186:189], v[126:129]
	v_mfma_f32_16x16x32_bf16 v[122:125], v[142:145], v[186:189], v[122:125]
	v_mfma_f32_16x16x32_bf16 v[114:117], v[134:137], v[194:197], v[114:117]
	v_mfma_f32_16x16x32_bf16 v[106:109], v[142:145], v[194:197], v[106:109]
	v_mfma_f32_16x16x32_bf16 v[98:101], v[134:137], v[202:205], v[98:101]
	v_mfma_f32_16x16x32_bf16 v[90:93], v[142:145], v[202:205], v[90:93]
	v_mfma_f32_16x16x32_bf16 v[82:85], v[134:137], v[226:229], v[82:85]
	v_mfma_f32_16x16x32_bf16 v[74:77], v[142:145], v[226:229], v[74:77]
	s_setprio 0
	s_setprio 1
	v_mfma_f32_16x16x32_bf16 v[118:121], v[146:149], v[172:175], v[118:121]
	v_mfma_f32_16x16x32_bf16 v[110:113], v[164:167], v[172:175], v[110:113]
	v_mfma_f32_16x16x32_bf16 v[102:105], v[146:149], v[190:193], v[102:105]
	v_mfma_f32_16x16x32_bf16 v[94:97], v[164:167], v[190:193], v[94:97]
	v_mfma_f32_16x16x32_bf16 v[86:89], v[146:149], v[198:201], v[86:89]
	v_mfma_f32_16x16x32_bf16 v[78:81], v[164:167], v[198:201], v[78:81]
	v_mfma_f32_16x16x32_bf16 v[70:73], v[146:149], v[206:209], v[70:73]
	v_mfma_f32_16x16x32_bf16 v[66:69], v[164:167], v[206:209], v[66:69]
	v_mfma_f32_16x16x32_bf16 v[118:121], v[160:163], v[186:189], v[118:121]
	v_mfma_f32_16x16x32_bf16 v[110:113], v[168:171], v[186:189], v[110:113]
	v_mfma_f32_16x16x32_bf16 v[102:105], v[160:163], v[194:197], v[102:105]
	v_mfma_f32_16x16x32_bf16 v[94:97], v[168:171], v[194:197], v[94:97]
	v_mfma_f32_16x16x32_bf16 v[86:89], v[160:163], v[202:205], v[86:89]
	v_mfma_f32_16x16x32_bf16 v[78:81], v[168:171], v[202:205], v[78:81]
	v_mfma_f32_16x16x32_bf16 v[70:73], v[160:163], v[226:229], v[70:73]
	v_mfma_f32_16x16x32_bf16 v[66:69], v[168:171], v[226:229], v[66:69]
	s_setprio 0
	s_barrier
	s_add_i32 s10, s12, s38
	v_lshl_add_u64 v[176:177], s[28:29], 0, v[64:65]
	s_mov_b32 m0, s10
	ds_read_b128 v[172:175], v184 offset:16384
	ds_read_b128 v[186:189], v184 offset:17408
	ds_read_b128 v[190:193], v184 offset:18432
	ds_read_b128 v[194:197], v184 offset:19456
	ds_read_b128 v[198:201], v184 offset:20480
	ds_read_b128 v[202:205], v184 offset:21504
	ds_read_b128 v[206:209], v184 offset:22528
	ds_read_b128 v[226:229], v184 offset:23552
	global_load_lds_dwordx4 v[176:177], off
	s_add_i32 m0, s10, 0x2000
	s_add_u32 s10, s28, 0x40000
	v_lshl_add_u64 v[230:231], s[28:29], 0, v[154:155]
	s_addc_u32 s11, s29, 0
	s_add_i32 s12, s13, s38
	global_load_lds_dwordx4 v[230:231], off
	v_lshl_add_u64 v[232:233], s[10:11], 0, v[64:65]
	s_mov_b32 m0, s12
	v_lshl_add_u64 v[244:245], s[36:37], 0, v[152:153]
	global_load_lds_dwordx4 v[232:233], off
	v_lshl_add_u64 v[232:233], s[10:11], 0, v[154:155]
	s_add_i32 m0, s12, 0x2000
	v_readlane_b32 s10, v251, 21
	global_load_lds_dwordx4 v[232:233], off
	v_lshl_add_u64 v[232:233], s[36:37], 0, v[150:151]
	s_mov_b32 m0, s25
	s_nop 0
	global_load_lds_dwordx4 v[232:233], off
	s_mov_b32 m0, s10
	s_nop 0
	global_load_lds_dwordx4 v[244:245], off
	s_waitcnt vmcnt(8)
	s_waitcnt lgkmcnt(0)
	s_barrier
	s_setprio 1
	s_waitcnt lgkmcnt(0)
	v_mfma_f32_16x16x32_bf16 v[60:63], v[130:133], v[172:175], v[60:63]
	v_mfma_f32_16x16x32_bf16 v[56:59], v[138:141], v[172:175], v[56:59]
	v_mfma_f32_16x16x32_bf16 v[48:51], v[130:133], v[190:193], v[48:51]
	v_mfma_f32_16x16x32_bf16 v[40:43], v[138:141], v[190:193], v[40:43]
	v_mfma_f32_16x16x32_bf16 v[32:35], v[130:133], v[198:201], v[32:35]
	v_mfma_f32_16x16x32_bf16 v[24:27], v[138:141], v[198:201], v[24:27]
	v_mfma_f32_16x16x32_bf16 v[16:19], v[130:133], v[206:209], v[16:19]
	v_mfma_f32_16x16x32_bf16 v[8:11], v[138:141], v[206:209], v[8:11]
	v_mfma_f32_16x16x32_bf16 v[60:63], v[134:137], v[186:189], v[60:63]
	v_mfma_f32_16x16x32_bf16 v[56:59], v[142:145], v[186:189], v[56:59]
	v_mfma_f32_16x16x32_bf16 v[48:51], v[134:137], v[194:197], v[48:51]
	v_mfma_f32_16x16x32_bf16 v[40:43], v[142:145], v[194:197], v[40:43]
	v_mfma_f32_16x16x32_bf16 v[32:35], v[134:137], v[202:205], v[32:35]
	v_mfma_f32_16x16x32_bf16 v[24:27], v[142:145], v[202:205], v[24:27]
	v_mfma_f32_16x16x32_bf16 v[16:19], v[134:137], v[226:229], v[16:19]
	v_mfma_f32_16x16x32_bf16 v[8:11], v[142:145], v[226:229], v[8:11]
	s_setprio 0
	s_setprio 1
	v_mfma_f32_16x16x32_bf16 v[52:55], v[146:149], v[172:175], v[52:55]
	v_mfma_f32_16x16x32_bf16 v[44:47], v[164:167], v[172:175], v[44:47]
	v_mfma_f32_16x16x32_bf16 v[36:39], v[146:149], v[190:193], v[36:39]
	v_mfma_f32_16x16x32_bf16 v[28:31], v[164:167], v[190:193], v[28:31]
	v_mfma_f32_16x16x32_bf16 v[20:23], v[146:149], v[198:201], v[20:23]
	v_mfma_f32_16x16x32_bf16 v[12:15], v[164:167], v[198:201], v[12:15]
	v_mfma_f32_16x16x32_bf16 v[4:7], v[146:149], v[206:209], v[4:7]
	v_mfma_f32_16x16x32_bf16 v[0:3], v[164:167], v[206:209], v[0:3]
	v_mfma_f32_16x16x32_bf16 v[52:55], v[160:163], v[186:189], v[52:55]
	v_mfma_f32_16x16x32_bf16 v[44:47], v[168:171], v[186:189], v[44:47]
	v_mfma_f32_16x16x32_bf16 v[36:39], v[160:163], v[194:197], v[36:39]
	v_mfma_f32_16x16x32_bf16 v[28:31], v[168:171], v[194:197], v[28:31]
	v_mfma_f32_16x16x32_bf16 v[20:23], v[160:163], v[202:205], v[20:23]
	v_mfma_f32_16x16x32_bf16 v[12:15], v[168:171], v[202:205], v[12:15]
	v_mfma_f32_16x16x32_bf16 v[4:7], v[160:163], v[226:229], v[4:7]
	v_mfma_f32_16x16x32_bf16 v[0:3], v[168:171], v[226:229], v[0:3]
	s_setprio 0
	s_barrier
	s_add_i32 s12, 0, 0x18000
	s_add_i32 s13, 0, 0x1c000
	v_add_u32_e32 v142, s12, v181
	v_add_u32_e32 v168, s13, v181
	ds_read_b128 v[130:133], v142
	ds_read_b128 v[134:137], v142 offset:1024
	ds_read_b128 v[138:141], v142 offset:2048
	ds_read_b128 v[142:145], v142 offset:3072
	ds_read_b128 v[146:149], v168
	ds_read_b128 v[160:163], v168 offset:1024
	ds_read_b128 v[164:167], v168 offset:2048
	ds_read_b128 v[168:171], v168 offset:3072
	s_add_u32 s10, s36, 0x40000
	s_addc_u32 s11, s37, 0
	s_mov_b32 m0, s75
	v_lshl_add_u64 v[210:211], s[10:11], 0, v[150:151]
	ds_read_b128 v[172:175], v184 offset:32768
	ds_read_b128 v[186:189], v184 offset:33792
	ds_read_b128 v[190:193], v184 offset:34816
	ds_read_b128 v[194:197], v184 offset:35840
	ds_read_b128 v[198:201], v184 offset:36864
	ds_read_b128 v[202:205], v184 offset:37888
	ds_read_b128 v[206:209], v184 offset:38912
	ds_read_b128 v[226:229], v184 offset:39936
	global_load_lds_dwordx4 v[210:211], off
	v_lshl_add_u64 v[210:211], s[10:11], 0, v[152:153]
	s_mov_b32 m0, s74
	s_nop 0
	global_load_lds_dwordx4 v[210:211], off
	s_waitcnt vmcnt(8)
	s_waitcnt lgkmcnt(0)
	s_barrier
	s_setprio 1
	s_waitcnt lgkmcnt(0)
	v_mfma_f32_16x16x32_bf16 v[126:129], v[130:133], v[172:175], v[126:129]
	v_mfma_f32_16x16x32_bf16 v[122:125], v[138:141], v[172:175], v[122:125]
	v_mfma_f32_16x16x32_bf16 v[114:117], v[130:133], v[190:193], v[114:117]
	v_mfma_f32_16x16x32_bf16 v[106:109], v[138:141], v[190:193], v[106:109]
	v_mfma_f32_16x16x32_bf16 v[98:101], v[130:133], v[198:201], v[98:101]
	v_mfma_f32_16x16x32_bf16 v[90:93], v[138:141], v[198:201], v[90:93]
	v_mfma_f32_16x16x32_bf16 v[82:85], v[130:133], v[206:209], v[82:85]
	v_mfma_f32_16x16x32_bf16 v[74:77], v[138:141], v[206:209], v[74:77]
	v_mfma_f32_16x16x32_bf16 v[126:129], v[134:137], v[186:189], v[126:129]
	v_mfma_f32_16x16x32_bf16 v[122:125], v[142:145], v[186:189], v[122:125]
	v_mfma_f32_16x16x32_bf16 v[114:117], v[134:137], v[194:197], v[114:117]
	v_mfma_f32_16x16x32_bf16 v[106:109], v[142:145], v[194:197], v[106:109]
	v_mfma_f32_16x16x32_bf16 v[98:101], v[134:137], v[202:205], v[98:101]
	v_mfma_f32_16x16x32_bf16 v[90:93], v[142:145], v[202:205], v[90:93]
	v_mfma_f32_16x16x32_bf16 v[82:85], v[134:137], v[226:229], v[82:85]
	v_mfma_f32_16x16x32_bf16 v[74:77], v[142:145], v[226:229], v[74:77]
	s_setprio 0
	s_setprio 1
	v_mfma_f32_16x16x32_bf16 v[118:121], v[146:149], v[172:175], v[118:121]
	v_mfma_f32_16x16x32_bf16 v[110:113], v[164:167], v[172:175], v[110:113]
	v_mfma_f32_16x16x32_bf16 v[102:105], v[146:149], v[190:193], v[102:105]
	v_mfma_f32_16x16x32_bf16 v[94:97], v[164:167], v[190:193], v[94:97]
	v_mfma_f32_16x16x32_bf16 v[86:89], v[146:149], v[198:201], v[86:89]
	v_mfma_f32_16x16x32_bf16 v[78:81], v[164:167], v[198:201], v[78:81]
	v_mfma_f32_16x16x32_bf16 v[70:73], v[146:149], v[206:209], v[70:73]
	v_mfma_f32_16x16x32_bf16 v[66:69], v[164:167], v[206:209], v[66:69]
	v_mfma_f32_16x16x32_bf16 v[118:121], v[160:163], v[186:189], v[118:121]
	v_mfma_f32_16x16x32_bf16 v[110:113], v[168:171], v[186:189], v[110:113]
	v_mfma_f32_16x16x32_bf16 v[102:105], v[160:163], v[194:197], v[102:105]
	v_mfma_f32_16x16x32_bf16 v[94:97], v[168:171], v[194:197], v[94:97]
	v_mfma_f32_16x16x32_bf16 v[86:89], v[160:163], v[202:205], v[86:89]
	v_mfma_f32_16x16x32_bf16 v[78:81], v[168:171], v[202:205], v[78:81]
	v_mfma_f32_16x16x32_bf16 v[70:73], v[160:163], v[226:229], v[70:73]
	v_mfma_f32_16x16x32_bf16 v[66:69], v[168:171], v[226:229], v[66:69]
	s_setprio 0
	s_barrier
	s_add_i32 s10, s12, s38
	v_lshl_add_u64 v[176:177], v[176:177], 0, s[42:43]
	s_mov_b32 m0, s10
	ds_read_b128 v[172:175], v184 offset:49152
	ds_read_b128 v[186:189], v184 offset:50176
	ds_read_b128 v[190:193], v184 offset:51200
	ds_read_b128 v[194:197], v184 offset:52224
	ds_read_b128 v[198:201], v184 offset:53248
	ds_read_b128 v[202:205], v184 offset:54272
	ds_read_b128 v[206:209], v184 offset:55296
	ds_read_b128 v[226:229], v184 offset:56320
	global_load_lds_dwordx4 v[176:177], off
	s_add_i32 m0, s10, 0x2000
	s_add_u32 s10, s28, 0x40080
	v_lshl_add_u64 v[176:177], v[230:231], 0, s[42:43]
	s_addc_u32 s11, s29, 0
	s_add_i32 s12, s13, s38
	global_load_lds_dwordx4 v[176:177], off
	v_lshl_add_u64 v[176:177], s[10:11], 0, v[64:65]
	s_mov_b32 m0, s12
	s_nop 0
	global_load_lds_dwordx4 v[176:177], off
	v_lshl_add_u64 v[176:177], s[10:11], 0, v[154:155]
	s_add_i32 m0, s12, 0x2000
	s_nop 0
	global_load_lds_dwordx4 v[176:177], off
	v_lshl_add_u64 v[176:177], v[232:233], 0, s[42:43]
	s_mov_b32 m0, s92
	s_nop 0
	global_load_lds_dwordx4 v[176:177], off
	v_lshl_add_u64 v[176:177], v[244:245], 0, s[42:43]
	s_mov_b32 m0, s78
	s_nop 0
	global_load_lds_dwordx4 v[176:177], off
	s_waitcnt vmcnt(8)
	s_waitcnt lgkmcnt(0)
	s_barrier
	s_setprio 1
	s_waitcnt lgkmcnt(0)
	v_mfma_f32_16x16x32_bf16 v[60:63], v[130:133], v[172:175], v[60:63]
	v_mfma_f32_16x16x32_bf16 v[56:59], v[138:141], v[172:175], v[56:59]
	v_mfma_f32_16x16x32_bf16 v[48:51], v[130:133], v[190:193], v[48:51]
	v_mfma_f32_16x16x32_bf16 v[40:43], v[138:141], v[190:193], v[40:43]
	v_mfma_f32_16x16x32_bf16 v[32:35], v[130:133], v[198:201], v[32:35]
	v_mfma_f32_16x16x32_bf16 v[24:27], v[138:141], v[198:201], v[24:27]
	v_mfma_f32_16x16x32_bf16 v[16:19], v[130:133], v[206:209], v[16:19]
	v_mfma_f32_16x16x32_bf16 v[8:11], v[138:141], v[206:209], v[8:11]
	v_mfma_f32_16x16x32_bf16 v[60:63], v[134:137], v[186:189], v[60:63]
	v_mfma_f32_16x16x32_bf16 v[56:59], v[142:145], v[186:189], v[56:59]
	v_mfma_f32_16x16x32_bf16 v[48:51], v[134:137], v[194:197], v[48:51]
	v_mfma_f32_16x16x32_bf16 v[40:43], v[142:145], v[194:197], v[40:43]
	v_mfma_f32_16x16x32_bf16 v[32:35], v[134:137], v[202:205], v[32:35]
	v_mfma_f32_16x16x32_bf16 v[24:27], v[142:145], v[202:205], v[24:27]
	v_mfma_f32_16x16x32_bf16 v[16:19], v[134:137], v[226:229], v[16:19]
	v_mfma_f32_16x16x32_bf16 v[8:11], v[142:145], v[226:229], v[8:11]
	s_setprio 0
	s_setprio 1
	v_mfma_f32_16x16x32_bf16 v[52:55], v[146:149], v[172:175], v[52:55]
	v_mfma_f32_16x16x32_bf16 v[44:47], v[164:167], v[172:175], v[44:47]
	v_mfma_f32_16x16x32_bf16 v[36:39], v[146:149], v[190:193], v[36:39]
	v_mfma_f32_16x16x32_bf16 v[28:31], v[164:167], v[190:193], v[28:31]
	v_mfma_f32_16x16x32_bf16 v[20:23], v[146:149], v[198:201], v[20:23]
	v_mfma_f32_16x16x32_bf16 v[12:15], v[164:167], v[198:201], v[12:15]
	v_mfma_f32_16x16x32_bf16 v[4:7], v[146:149], v[206:209], v[4:7]
	v_mfma_f32_16x16x32_bf16 v[0:3], v[164:167], v[206:209], v[0:3]
	v_mfma_f32_16x16x32_bf16 v[52:55], v[160:163], v[186:189], v[52:55]
	v_mfma_f32_16x16x32_bf16 v[44:47], v[168:171], v[186:189], v[44:47]
	v_mfma_f32_16x16x32_bf16 v[36:39], v[160:163], v[194:197], v[36:39]
	v_mfma_f32_16x16x32_bf16 v[28:31], v[168:171], v[194:197], v[28:31]
	v_mfma_f32_16x16x32_bf16 v[20:23], v[160:163], v[202:205], v[20:23]
	v_mfma_f32_16x16x32_bf16 v[12:15], v[168:171], v[202:205], v[12:15]
	v_mfma_f32_16x16x32_bf16 v[4:7], v[160:163], v[226:229], v[4:7]
	v_mfma_f32_16x16x32_bf16 v[0:3], v[168:171], v[226:229], v[0:3]
	s_setprio 0
	s_add_i32 s9, s9, 2
	s_add_u32 s52, s52, 0x100
	s_addc_u32 s53, s53, 0
	s_add_u32 s7, s7, 0x100
	s_addc_u32 s8, s8, 0
	s_cmp_gt_u32 s9, 13
	s_barrier
	s_cbranch_scc0 .LBB0_789
	s_and_b64 vcc, exec, s[18:19]
	s_cbranch_vccz .LBB0_792
	s_barrier
